# C loop: tile-end barriers placed before and after the LDS tile writes instead of back to back; rest as v24
# speedup vs baseline: 1.0061x; 1.0061x over previous
; DI float ex2(float x) { return __builtin_amdgcn_exp2f(x); }
; #define MFMA32(a, b, c) __builtin_amdgcn_mfma_f32_32x32x16_bf16((a), (b), (c), 0, 0, 0)
; template <int MODE>
; DI void attn_unit(unsigned char* lds, const AttnParams& ap, int b, int h, int qb, int tid) {
;     ...
;     if (MODE == 1) {
; #pragma unroll
;       for (int kh = 0; kh < 2; ++kh) {
;         const bf16_t* kb = Ks + (32 * kh + r32) * 72 + 8 * hi;
;         bf16x8 p0[2], p1[2];
;         { f32x16 s0 = splat16(ap.negM);
;           s0 = MFMA32(*(const bf16x8*)(kb), qf[0], s0); s0 = MFMA32(*(const bf16x8*)(kb + 16), qf[1], s0);
; #pragma unroll
;           for (int i = 0; i < 16; ++i) { s0[i] = ex2(s0[i]); l0 += s0[i]; }
;           p0[0] = pack8(s0, 0); p0[1] = pack8(s0, 1); }
;         { f32x16 s1 = splat16(ap.negM);
;           s1 = MFMA32(*(const bf16x8*)(kb + 32), qf[2], s1); s1 = MFMA32(*(const bf16x8*)(kb + 48), qf[3], s1);
; #pragma unroll
;           for (int i = 0; i < 16; ++i) { s1[i] = ex2(s1[i]); l1 += s1[i]; }
;           p1[0] = pack8(s1, 0); p1[1] = pack8(s1, 1); }
; #pragma unroll
;         for (int kk = 0; kk < 2; ++kk) {
; #pragma unroll
;           for (int eb = 0; eb < 2; ++eb) { const bf16_t* vb = Vs + (32 * eb + r32) * 72 + 32 * kh + 16 * kk + 8 * hi; const bf16x8 vf = *(const bf16x8*)vb;
;             O0[eb] = MFMA32(vf, p0[kk], O0[eb]); O1[eb] = MFMA32(vf, p1[kk], O1[eb]); } }
.Lc_tile_loop:
	global_load_dwordx4 v[204:207], v[138:139], off
	global_load_dwordx4 v[142:145], v[136:137], off
	v_lshl_add_u64 v[138:139], v[138:139], 0, s[2:3]
	v_lshl_add_u64 v[136:137], v[136:137], 0, s[18:19]
	s_waitcnt lgkmcnt(0)
	v_mfma_f32_32x32x16_bf16 v[116:131], v[166:169], v[38:41], v[48:63]
	v_exp_f32_e32 v96, v96
	v_exp_f32_e32 v97, v97
	v_exp_f32_e32 v98, v98
	v_exp_f32_e32 v99, v99
	v_mfma_f32_32x32x16_bf16 v[116:131], v[170:173], v[34:37], v[116:131]
	v_exp_f32_e32 v100, v100
	v_exp_f32_e32 v101, v101
	v_exp_f32_e32 v102, v102
	v_exp_f32_e32 v103, v103
	ds_read_b128 v[166:169], v32 offset:4608
	ds_read_b128 v[170:173], v32 offset:4640
	v_mfma_f32_32x32x16_bf16 v[80:95], v[174:177], v[158:161], v[80:95]
	v_exp_f32_e32 v104, v104
	v_exp_f32_e32 v105, v105
	v_add_f32_e32 v141, v141, v96
	v_add_f32_e32 v150, v150, v97
	v_add_f32_e32 v141, v141, v98
	v_add_f32_e32 v150, v150, v99
	v_mfma_f32_32x32x16_bf16 v[16:31], v[182:185], v[158:161], v[16:31]
	v_exp_f32_e32 v106, v106
	v_exp_f32_e32 v107, v107
	v_cvt_pk_bf16_f32 v158, v96, v97
	v_cvt_pk_bf16_f32 v159, v98, v99
	v_add_f32_e32 v141, v141, v100
	v_add_f32_e32 v150, v150, v101
	v_mfma_f32_32x32x16_bf16 v[80:95], v[178:181], v[162:165], v[80:95]
	v_exp_f32_e32 v108, v108
	v_exp_f32_e32 v109, v109
	v_cvt_pk_bf16_f32 v160, v100, v101
	v_cvt_pk_bf16_f32 v161, v102, v103
	v_add_f32_e32 v141, v141, v102
	v_add_f32_e32 v150, v150, v103
	v_mfma_f32_32x32x16_bf16 v[16:31], v[186:189], v[162:165], v[16:31]
	ds_read_b128 v[174:177], v32 offset:9216
	ds_read_b128 v[178:181], v32 offset:9248
	ds_read_b128 v[182:185], v32 offset:13824
	ds_read_b128 v[186:189], v32 offset:13856
	v_exp_f32_e32 v110, v110
	v_exp_f32_e32 v111, v111
	v_add_f32_e32 v141, v141, v104
	v_add_f32_e32 v150, v150, v105
	v_add_f32_e32 v141, v141, v106
	v_add_f32_e32 v150, v150, v107
	v_add_f32_e32 v141, v141, v108
	v_add_f32_e32 v150, v150, v109
	v_cvt_pk_bf16_f32 v162, v104, v105
	v_cvt_pk_bf16_f32 v163, v106, v107
	v_cvt_pk_bf16_f32 v164, v108, v109
	v_add_f32_e32 v141, v141, v110
	v_add_f32_e32 v150, v150, v111
	v_cvt_pk_bf16_f32 v165, v110, v111
	s_waitcnt lgkmcnt(0)
	v_mfma_f32_32x32x16_bf16 v[96:111], v[166:169], v[112:115], v[48:63]
	v_exp_f32_e32 v116, v116
	v_exp_f32_e32 v117, v117
	v_exp_f32_e32 v118, v118
	v_exp_f32_e32 v119, v119
	v_mfma_f32_32x32x16_bf16 v[96:111], v[170:173], v[42:45], v[96:111]
	v_exp_f32_e32 v120, v120
	v_exp_f32_e32 v121, v121
	v_exp_f32_e32 v122, v122
	v_exp_f32_e32 v123, v123
	ds_read_b128 v[166:169], v32 offset:4672
	ds_read_b128 v[170:173], v32 offset:4704
	v_mfma_f32_32x32x16_bf16 v[64:79], v[174:177], v[158:161], v[64:79]
	v_exp_f32_e32 v124, v124
	v_exp_f32_e32 v125, v125
	v_add_f32_e32 v140, v140, v116
	v_add_f32_e32 v151, v151, v117
	v_add_f32_e32 v140, v140, v118
	v_add_f32_e32 v151, v151, v119
	v_mfma_f32_32x32x16_bf16 v[0:15], v[182:185], v[158:161], v[0:15]
	v_exp_f32_e32 v126, v126
	v_exp_f32_e32 v127, v127
	v_cvt_pk_bf16_f32 v158, v116, v117
	v_cvt_pk_bf16_f32 v159, v118, v119
	v_add_f32_e32 v140, v140, v120
	v_add_f32_e32 v151, v151, v121
	v_mfma_f32_32x32x16_bf16 v[64:79], v[178:181], v[162:165], v[64:79]
	v_exp_f32_e32 v128, v128
	v_exp_f32_e32 v129, v129
	v_cvt_pk_bf16_f32 v160, v120, v121
	v_cvt_pk_bf16_f32 v161, v122, v123
	v_add_f32_e32 v140, v140, v122
	v_add_f32_e32 v151, v151, v123
	v_mfma_f32_32x32x16_bf16 v[0:15], v[186:189], v[162:165], v[0:15]
	v_exp_f32_e32 v130, v130
	v_exp_f32_e32 v131, v131
	v_add_f32_e32 v140, v140, v124
	v_add_f32_e32 v151, v151, v125
	v_add_f32_e32 v140, v140, v126
	v_add_f32_e32 v151, v151, v127
	v_add_f32_e32 v140, v140, v128
	v_add_f32_e32 v151, v151, v129
	v_cvt_pk_bf16_f32 v162, v124, v125
	v_cvt_pk_bf16_f32 v163, v126, v127
	v_cvt_pk_bf16_f32 v164, v128, v129
	v_add_f32_e32 v140, v140, v130
	v_add_f32_e32 v151, v151, v131
	v_cvt_pk_bf16_f32 v165, v130, v131
	s_waitcnt lgkmcnt(0)
; DI float ex2(float x) { return __builtin_amdgcn_exp2f(x); }
; template <int MODE>
; DI void attn_unit(unsigned char* lds, const AttnParams& ap, int b, int h, int qb, int tid) {
;     ...
;   for (int n = 0; n < ntiles; n += NCH) {
;     const int jb = (MODE == 2) ? jhi - n : jlo + n;
;     __syncthreads();
;     if (MODE == 2 && D_EARLY) { int alld = 1;
; #pragma unroll
;       for (int w = 0; w < 8; ++w) alld &= flags[w];
;       if (alld) break; }
; #pragma unroll
;     for (int c = 0; c < NCH; ++c) { *(u32x4*)(Ks0 + (c * 64 + lrow) * 72 + 8 * lch) = kreg[c]; *(u32x4*)(Vs0 + (c * 64 + lrow) * 72 + 8 * lch) = vreg[c]; }
;     __syncthreads();
;     if (n + NCH < ntiles) {
; #pragma unroll
;       for (int c = 0; c < NCH; ++c) { const int jn = (MODE == 2) ? jb - NCH - c : jb + NCH + c; kreg[c] = *(const u32x4*)(kg + (size_t)jn * 64 * PLD); vreg[c] = *(const u32x4*)(vg + (size_t)jn * 4096); } }
; #pragma unroll
;     for (int c = 0; c < NCH; ++c) {
;     const int j = (MODE == 2) ? jb - c : jb + c;
;     const bf16_t* Ks = Ks0 + c * 64 * 72; const bf16_t* Vs = Vs0 + c * 64 * 72;
;     const bool active = (j <= cw) && (MODE != 0 || j >= cw - 8);
;     if (!active) continue;
;     if (MODE == 2 && D_EARLY && wdone) continue;
;     if (MODE == 1) {
; #pragma unroll
;       for (int kh = 0; kh < 2; ++kh) {
;         const bf16_t* kb = Ks + (32 * kh + r32) * 72 + 8 * hi;
;         bf16x8 p0[2], p1[2];
;         { f32x16 s0 = splat16(ap.negM);
;           s0 = MFMA32(*(const bf16x8*)(kb), qf[0], s0); s0 = MFMA32(*(const bf16x8*)(kb + 16), qf[1], s0);
; #pragma unroll
;           for (int i = 0; i < 16; ++i) { s0[i] = ex2(s0[i]); l0 += s0[i]; }
;           p0[0] = pack8(s0, 0); p0[1] = pack8(s0, 1); }
;         { f32x16 s1 = splat16(ap.negM);
;           s1 = MFMA32(*(const bf16x8*)(kb + 32), qf[2], s1); s1 = MFMA32(*(const bf16x8*)(kb + 48), qf[3], s1);
; #pragma unroll
;           for (int i = 0; i < 16; ++i) { s1[i] = ex2(s1[i]); l1 += s1[i]; }
;           p1[0] = pack8(s1, 0); p1[1] = pack8(s1, 1); }
; #pragma unroll
;         for (int kk = 0; kk < 2; ++kk) {
; #pragma unroll
;           for (int eb = 0; eb < 2; ++eb) { const bf16_t* vb = Vs + (32 * eb + r32) * 72 + 32 * kh + 16 * kk + 8 * hi; const bf16x8 vf = *(const bf16x8*)vb;
;             O0[eb] = MFMA32(vf, p0[kk], O0[eb]); O1[eb] = MFMA32(vf, p1[kk], O1[eb]); } }
;       }
	v_mfma_f32_32x32x16_bf16 v[116:131], v[166:169], v[38:41], v[48:63]
	v_exp_f32_e32 v96, v96
	v_exp_f32_e32 v97, v97
	v_exp_f32_e32 v98, v98
	v_exp_f32_e32 v99, v99
	v_mfma_f32_32x32x16_bf16 v[116:131], v[170:173], v[34:37], v[116:131]
	v_exp_f32_e32 v100, v100
	v_exp_f32_e32 v101, v101
	v_exp_f32_e32 v102, v102
	v_exp_f32_e32 v103, v103
	ds_read_b128 v[166:169], v157
	ds_read_b128 v[170:173], v157 offset:32
	v_mfma_f32_32x32x16_bf16 v[80:95], v[174:177], v[158:161], v[80:95]
	v_exp_f32_e32 v104, v104
	v_exp_f32_e32 v105, v105
	v_add_f32_e32 v141, v141, v96
	v_add_f32_e32 v150, v150, v97
	v_add_f32_e32 v141, v141, v98
	v_add_f32_e32 v150, v150, v99
	v_mfma_f32_32x32x16_bf16 v[16:31], v[182:185], v[158:161], v[16:31]
	v_exp_f32_e32 v106, v106
	v_exp_f32_e32 v107, v107
	v_cvt_pk_bf16_f32 v158, v96, v97
	v_cvt_pk_bf16_f32 v159, v98, v99
	v_add_f32_e32 v141, v141, v100
	v_add_f32_e32 v150, v150, v101
	v_mfma_f32_32x32x16_bf16 v[80:95], v[178:181], v[162:165], v[80:95]
	v_exp_f32_e32 v108, v108
	v_exp_f32_e32 v109, v109
	v_cvt_pk_bf16_f32 v160, v100, v101
	v_cvt_pk_bf16_f32 v161, v102, v103
	v_add_f32_e32 v141, v141, v102
	v_add_f32_e32 v150, v150, v103
	v_mfma_f32_32x32x16_bf16 v[16:31], v[186:189], v[162:165], v[16:31]
	ds_read_b128 v[174:177], v32 offset:9280
	ds_read_b128 v[178:181], v32 offset:9312
	ds_read_b128 v[182:185], v32 offset:13888
	ds_read_b128 v[186:189], v32 offset:13920
	v_exp_f32_e32 v110, v110
	v_exp_f32_e32 v111, v111
	v_add_f32_e32 v141, v141, v104
	v_add_f32_e32 v150, v150, v105
	v_add_f32_e32 v141, v141, v106
	v_add_f32_e32 v150, v150, v107
	v_add_f32_e32 v141, v141, v108
	v_add_f32_e32 v150, v150, v109
	v_cvt_pk_bf16_f32 v162, v104, v105
	v_cvt_pk_bf16_f32 v163, v106, v107
	v_cvt_pk_bf16_f32 v164, v108, v109
	v_add_f32_e32 v141, v141, v110
	v_add_f32_e32 v150, v150, v111
	v_cvt_pk_bf16_f32 v165, v110, v111
	s_waitcnt lgkmcnt(0)
	v_mfma_f32_32x32x16_bf16 v[96:111], v[166:169], v[112:115], v[48:63]
	v_exp_f32_e32 v116, v116
	v_exp_f32_e32 v117, v117
	v_exp_f32_e32 v118, v118
	v_exp_f32_e32 v119, v119
	v_mfma_f32_32x32x16_bf16 v[96:111], v[170:173], v[42:45], v[96:111]
	v_exp_f32_e32 v120, v120
	v_exp_f32_e32 v121, v121
	v_exp_f32_e32 v122, v122
	v_exp_f32_e32 v123, v123
	ds_read_b128 v[166:169], v157 offset:64
	ds_read_b128 v[170:173], v157 offset:96
	v_mfma_f32_32x32x16_bf16 v[64:79], v[174:177], v[158:161], v[64:79]
	v_exp_f32_e32 v124, v124
	v_exp_f32_e32 v125, v125
	v_add_f32_e32 v140, v140, v116
	v_add_f32_e32 v151, v151, v117
	v_add_f32_e32 v140, v140, v118
	v_add_f32_e32 v151, v151, v119
	v_mfma_f32_32x32x16_bf16 v[0:15], v[182:185], v[158:161], v[0:15]
	v_exp_f32_e32 v126, v126
	v_exp_f32_e32 v127, v127
	v_cvt_pk_bf16_f32 v158, v116, v117
	v_cvt_pk_bf16_f32 v159, v118, v119
	v_add_f32_e32 v140, v140, v120
	v_add_f32_e32 v151, v151, v121
	v_mfma_f32_32x32x16_bf16 v[64:79], v[178:181], v[162:165], v[64:79]
	v_exp_f32_e32 v128, v128
	v_exp_f32_e32 v129, v129
	v_cvt_pk_bf16_f32 v160, v120, v121
	v_cvt_pk_bf16_f32 v161, v122, v123
	v_add_f32_e32 v140, v140, v122
	v_add_f32_e32 v151, v151, v123
	v_mfma_f32_32x32x16_bf16 v[0:15], v[186:189], v[162:165], v[0:15]
	v_exp_f32_e32 v130, v130
	v_exp_f32_e32 v131, v131
	v_add_f32_e32 v140, v140, v124
	v_add_f32_e32 v151, v151, v125
	v_add_f32_e32 v140, v140, v126
	v_add_f32_e32 v151, v151, v127
	v_add_f32_e32 v140, v140, v128
	v_add_f32_e32 v151, v151, v129
	v_cvt_pk_bf16_f32 v162, v124, v125
	v_cvt_pk_bf16_f32 v163, v126, v127
	v_cvt_pk_bf16_f32 v164, v128, v129
	v_add_f32_e32 v140, v140, v130
	v_add_f32_e32 v151, v151, v131
	v_cvt_pk_bf16_f32 v165, v130, v131
	s_waitcnt vmcnt(0)
	s_barrier
	ds_write_b128 v146, v[204:207]
	ds_write_b128 v146, v[142:145] offset:9216
	s_mov_b32 s0, s9
	s_mov_b32 s9, s10
	s_mov_b32 s10, s11
	s_mov_b32 s11, s0
	v_mov_b32_e32 v32, v157
	v_add_u32_e32 v157, s10, v133
	v_add_u32_e32 v146, s11, v190
	s_add_i32 s4, s4, 1
	s_waitcnt lgkmcnt(0)
	s_barrier
	s_cmp_le_u32 s4, s5
	s_cbranch_scc1 .Lc_tile_loop
	v_mfma_f32_32x32x16_bf16 v[80:95], v[174:177], v[158:161], v[80:95]
	v_mfma_f32_32x32x16_bf16 v[16:31], v[182:185], v[158:161], v[16:31]
	v_mfma_f32_32x32x16_bf16 v[80:95], v[178:181], v[162:165], v[80:95]
	v_mfma_f32_32x32x16_bf16 v[16:31], v[186:189], v[162:165], v[16:31]
	s_cmp_gt_u32 s4, s8
	s_cbranch_scc1 .Lc_tiles_done
.Lc_idle_loop:
	global_load_dwordx4 v[204:207], v[138:139], off
	global_load_dwordx4 v[142:145], v[136:137], off
	v_lshl_add_u64 v[138:139], v[138:139], 0, s[2:3]
	v_lshl_add_u64 v[136:137], v[136:137], 0, s[18:19]
	s_waitcnt vmcnt(0)
	s_barrier
	ds_write_b128 v146, v[204:207]
	ds_write_b128 v146, v[142:145] offset:9216
	s_mov_b32 s0, s9
	s_mov_b32 s9, s10
	s_mov_b32 s10, s11
	s_mov_b32 s11, s0
	v_add_u32_e32 v146, s11, v190
	s_add_i32 s4, s4, 1
	s_waitcnt lgkmcnt(0)
	s_barrier
	s_cmp_le_u32 s4, s8
	s_cbranch_scc1 .Lc_idle_loop
